# P3: static s_setprio 1 for waves 4-7 during the token-mixer phase
# baseline (speedup 1.0000x reference)
; DEVI int opaque_tid(int wv) { int t; asm volatile("v_mbcnt_lo_u32_b32 %0, -1, 0\n\tv_mbcnt_hi_u32_b32 %0, -1, %0" : "=v"(t)); return wv * 64 + t; }
; __global__ void __launch_bounds__(512) mega(Params p) {
;     ...
;   auto shadow_step = [&]() {
;     int bido = bid; asm volatile("" : "+s"(bido));
;     if (sph <= 20 && sph % 5 == 0 && sph > 0 && bido < 16) {
;       const int tid = opaque_tid(wv);
;       for (int k = tid; k < DM; k += 512) SNAP[(size_t)((sph / 5 - 1) * 16 + bido) * 1024 + k] = SX[bido * 1024 + k];
;     }
.LBB0_995:
	s_or_b64 exec, exec, s[0:1]
	v_readlane_b32 s0, v254, 54
	s_add_i32 s9, s0, 2
	s_mul_hi_u32 s0, s9, 0xcccccccd
	s_lshr_b32 s0, s0, 2
	s_mul_i32 s0, s0, 5
	s_sub_i32 s21, s9, s0
	s_mov_b32 s20, s76
	s_cmp_eq_u32 s21, 0
	s_barrier
	s_cselect_b64 s[0:1], -1, 0
	s_cmp_lt_i32 s20, 16
	s_cselect_b64 s[2:3], -1, 0
	v_readlane_b32 vcc_lo, v252, 46
	s_nop 3
	s_cmp_ge_u32 vcc_lo, 0x100
	s_cbranch_scc0 .Lp3prio_skip
	s_setprio 1
.Lp3prio_skip:
	s_and_b64 s[0:1], s[0:1], s[2:3]
	s_andn2_b64 vcc, exec, s[0:1]
	s_cbranch_vccnz .LBB0_1000
	v_readlane_b32 s0, v252, 46
	v_mbcnt_lo_u32_b32 v0, -1, 0
	v_mbcnt_hi_u32_b32 v0, -1, v0
	s_nop 1
	v_add_u32_e32 v2, s0, v0
	s_movk_i32 s0, 0x400
	v_cmp_gt_i32_e32 vcc, s0, v2
	s_and_saveexec_b64 s[0:1], vcc
	s_mov_b64 s[6:7], 0x800
	s_cbranch_execz .LBB0_999
	v_readlane_b32 s2, v254, 55
	s_mul_hi_u32 s2, s2, 0xcccccccd
	s_lshl_b32 s2, s2, 2
	s_and_b32 s2, s2, -16
	v_readlane_b32 s3, v254, 56
	s_add_i32 s2, s20, s2
	v_readlane_b32 s3, v254, 28
	s_add_i32 s2, s2, -16
	v_readlane_b32 s4, v253, 20
	v_add_u32_e32 v4, s3, v0
	s_ashr_i32 s3, s2, 31
	s_lshl_b64 s[2:3], s[2:3], 12
	s_add_u32 s2, s4, s2
	v_readlane_b32 s4, v253, 21
	v_ashrrev_i32_e32 v3, 31, v2
	s_addc_u32 s3, s4, s3
	v_lshl_add_u64 v[0:1], v[2:3], 2, s[2:3]
	v_lshl_add_u32 v2, s20, 10, v2
	v_readlane_b32 s2, v253, 12
	v_ashrrev_i32_e32 v3, 31, v2
	v_readlane_b32 s3, v253, 13
	s_mov_b64 s[4:5], 0
	s_nop 0
	v_lshl_add_u64 v[2:3], v[2:3], 2, s[2:3]

; DEVI int opaque_tid(int wv) { int t; asm volatile("v_mbcnt_lo_u32_b32 %0, -1, 0\n\tv_mbcnt_hi_u32_b32 %0, -1, %0" : "=v"(t)); return wv * 64 + t; }
; DEVI void gbar(unsigned* ctr, unsigned& gen, int wv) {
;   asm volatile("s_waitcnt vmcnt(0) lgkmcnt(0)" ::: "memory");
;   __syncthreads();
;   ++gen;
;   const int tb = opaque_tid(wv);
;   if (tb < 64) {
;     __builtin_amdgcn_fence(__ATOMIC_RELEASE, "agent");
;     asm volatile("s_waitcnt vmcnt(0)" ::: "memory");
;     if (tb == 0) {
;       __hip_atomic_fetch_add(ctr, 1u, __ATOMIC_RELAXED, __HIP_MEMORY_SCOPE_AGENT);
;       const unsigned target = gen * 256u;
;       while (__hip_atomic_load(ctr, __ATOMIC_RELAXED, __HIP_MEMORY_SCOPE_AGENT) < target) { }
.LBB0_1496:
	s_setprio 0
	s_waitcnt vmcnt(0) lgkmcnt(0)
	s_barrier
	v_mbcnt_lo_u32_b32 v0, -1, 0
	v_mbcnt_hi_u32_b32 v0, -1, v0
	v_readlane_b32 s0, v252, 46
	s_nop 1
	v_add_u32_e32 v0, s0, v0
	v_cmp_gt_i32_e32 vcc, 64, v0
	s_mov_b64 s[0:1], exec
	v_readlane_b32 s76, v253, 4
	v_readlane_b32 s77, v253, 5
	v_readlane_b32 s52, v255, 1
	v_readlane_b32 s54, v253, 22
	v_readlane_b32 s56, v253, 24
	s_and_b64 s[2:3], s[0:1], vcc
	v_readlane_b32 s53, v255, 2
	v_readlane_b32 s55, v253, 23
	v_readlane_b32 s57, v253, 25
	v_readlane_b32 s65, v255, 3
	s_movk_i32 s74, 0xffc0
	v_readlane_b32 s59, v255, 4
	v_readlane_b32 s64, v255, 5
	s_movk_i32 s75, 0x2ff
	s_mov_b32 s77, 0x800000
	s_mov_b32 s78, 0xfffe4000
	s_mov_b32 s79, 0xfffe8000
	s_mov_b32 s80, 0xfffec000
	s_mov_b32 s81, 0xffff0000
	s_mov_b32 s82, 0xffff4000
	s_movk_i32 s83, 0x8000
	s_movk_i32 s84, 0xc000
	s_movk_i32 s70, 0x140
	s_movk_i32 s85, 0xa000
	s_movk_i32 s86, 0xb000
	s_movk_i32 s87, 0xe000
	s_mov_b64 exec, s[2:3]
	s_cbranch_execz .LBB0_1503
	s_waitcnt vmcnt(0)
	v_cmp_eq_u32_e32 vcc, 0, v0
	s_and_saveexec_b64 s[4:5], vcc
	s_cbranch_execz .LBB0_1502
	s_getreg_b32 s8, hwreg(HW_REG_XCC_ID, 0, 4)
	s_lshl_b32 s8, s8, 2
	s_add_u32 s8, s52, s8
	s_addc_u32 s9, s53, 0
	v_mov_b32_e32 v0, 1
	global_atomic_add v0, v33, v0, s[8:9] offset:128 sc0
	v_readlane_b32 s2, v254, 48
	s_lshl_b32 s2, s2, 5
	s_addk_i32 s2, 96
	s_waitcnt vmcnt(0)
	v_readfirstlane_b32 s6, v0
	s_add_i32 s6, s6, 1
	s_cmp_lg_u32 s6, s2
	s_cbranch_scc1 .Lgb3_poll
	buffer_wbl2 sc1
	s_waitcnt vmcnt(0)
	v_mov_b32_e32 v0, 1
	global_atomic_add v33, v0, s[52:53]
